# v9 with non-temporal (nt) hint on the P0 x / p streaming loads
# speedup vs baseline: 1.0024x; 1.0022x over previous
.LBB0_132:
	s_and_b64 vcc, exec, s[96:97]
	s_cbranch_vccz .LBB0_137
	v_readlane_b32 s36, v249, 6
	v_readlane_b32 s37, v249, 7
	v_readlane_b32 s38, v249, 8
	v_readlane_b32 s39, v249, 9
	v_readlane_b32 s40, v249, 10
	v_readlane_b32 s41, v249, 11
	v_readlane_b32 s42, v249, 12
	v_readlane_b32 s43, v249, 13
	v_readlane_b32 s44, v249, 22
	v_readlane_b32 s45, v249, 23
	v_readlane_b32 s46, v248, 11
	v_readlane_b32 s47, v248, 12
	v_readlane_b32 s48, v248, 9
	v_readlane_b32 s49, v248, 10
	v_lshlrev_b32_e32 v1, 4, v184
	v_lshlrev_b32_e32 v2, 3, v184
	v_mov_b32_e32 v3, 0x358637bd
	s_nop 2
	global_load_dwordx4 v[6:9], v1, s[44:45] offset:0
	global_load_dwordx4 v[10:13], v1, s[44:45] offset:1024
	global_load_dwordx4 v[14:17], v1, s[44:45] offset:2048
	global_load_dwordx4 v[18:21], v1, s[44:45] offset:3072
	s_mov_b32 s0, s30
	s_mov_b32 s1, s54
	s_mov_b32 s15, s0
	s_cmp_lt_u32 s15, 0x8400
	s_cselect_b32 s12, s15, s0
	s_cmp_lt_u32 s12, 0x8000
	s_cselect_b32 s8, s36, s38
	s_cselect_b32 s9, s37, s39
	s_cselect_b32 s10, s40, s42
	s_cselect_b32 s11, s41, s43
	s_cselect_b32 s13, 0, 0x8000
	s_sub_u32 s12, s12, s13
	s_lshl_b32 s13, s12, 12
	s_add_u32 s8, s8, s13
	s_addc_u32 s9, s9, 0
	s_lshl_b32 s13, s12, 10
	s_add_u32 s10, s10, s13
	s_addc_u32 s11, s11, 0
	global_load_dwordx4 v[24:27], v1, s[8:9] offset:0 nt
	global_load_dwordx4 v[28:31], v1, s[8:9] offset:1024 nt
	global_load_dwordx4 v[32:35], v1, s[8:9] offset:2048 nt
	global_load_dwordx4 v[36:39], v1, s[8:9] offset:3072 nt
	global_load_dwordx4 v[40:43], v1, s[10:11] nt
	s_add_i32 s15, s15, s1
	s_cmp_lt_u32 s15, 0x8400
	s_cselect_b32 s12, s15, s0
	s_cmp_lt_u32 s12, 0x8000
	s_cselect_b32 s8, s36, s38
	s_cselect_b32 s9, s37, s39
	s_cselect_b32 s10, s40, s42
	s_cselect_b32 s11, s41, s43
	s_cselect_b32 s13, 0, 0x8000
	s_sub_u32 s12, s12, s13
	s_lshl_b32 s13, s12, 12
	s_add_u32 s8, s8, s13
	s_addc_u32 s9, s9, 0
	s_lshl_b32 s13, s12, 10
	s_add_u32 s10, s10, s13
	s_addc_u32 s11, s11, 0
	global_load_dwordx4 v[44:47], v1, s[8:9] offset:0 nt
	global_load_dwordx4 v[48:51], v1, s[8:9] offset:1024 nt
	global_load_dwordx4 v[52:55], v1, s[8:9] offset:2048 nt
	global_load_dwordx4 v[56:59], v1, s[8:9] offset:3072 nt
	global_load_dwordx4 v[60:63], v1, s[10:11] nt
	s_add_i32 s15, s15, s1
	s_cmp_lt_u32 s15, 0x8400
	s_cselect_b32 s12, s15, s0
	s_cmp_lt_u32 s12, 0x8000
	s_cselect_b32 s8, s36, s38
	s_cselect_b32 s9, s37, s39
	s_cselect_b32 s10, s40, s42
	s_cselect_b32 s11, s41, s43
	s_cselect_b32 s13, 0, 0x8000
	s_sub_u32 s12, s12, s13
	s_lshl_b32 s13, s12, 12
	s_add_u32 s8, s8, s13
	s_addc_u32 s9, s9, 0
	s_lshl_b32 s13, s12, 10
	s_add_u32 s10, s10, s13
	s_addc_u32 s11, s11, 0
	global_load_dwordx4 v[64:67], v1, s[8:9] offset:0 nt
	global_load_dwordx4 v[68:71], v1, s[8:9] offset:1024 nt
	global_load_dwordx4 v[72:75], v1, s[8:9] offset:2048 nt
	global_load_dwordx4 v[76:79], v1, s[8:9] offset:3072 nt
	global_load_dwordx4 v[80:83], v1, s[10:11] nt
	s_add_i32 s15, s15, s1
	s_cmp_lt_u32 s15, 0x8400
	s_cselect_b32 s12, s15, s0
	s_cmp_lt_u32 s12, 0x8000
	s_cselect_b32 s8, s36, s38
	s_cselect_b32 s9, s37, s39
	s_cselect_b32 s10, s40, s42
	s_cselect_b32 s11, s41, s43
	s_cselect_b32 s13, 0, 0x8000
	s_sub_u32 s12, s12, s13
	s_lshl_b32 s13, s12, 12
	s_add_u32 s8, s8, s13
	s_addc_u32 s9, s9, 0
	s_lshl_b32 s13, s12, 10
	s_add_u32 s10, s10, s13
	s_addc_u32 s11, s11, 0
	global_load_dwordx4 v[84:87], v1, s[8:9] offset:0 nt
	global_load_dwordx4 v[88:91], v1, s[8:9] offset:1024 nt
	global_load_dwordx4 v[92:95], v1, s[8:9] offset:2048 nt
	global_load_dwordx4 v[96:99], v1, s[8:9] offset:3072 nt
	global_load_dwordx4 v[100:103], v1, s[10:11] nt
	s_add_i32 s15, s15, s1
	s_mul_i32 s8, s1, 3
	s_add_i32 s8, s8, s0
	s_cmp_lt_u32 s8, 0x8400
	s_cbranch_scc0 .Lxn_tail
	s_mov_b32 s14, s0
	s_waitcnt vmcnt(15)
	v_mul_f32_e32 v4, v24, v24
	v_mul_f32_e32 v5, v25, v25
	v_fmac_f32_e32 v4, v26, v26
	v_fmac_f32_e32 v5, v27, v27
	v_fmac_f32_e32 v4, v28, v28
	v_fmac_f32_e32 v5, v29, v29
	v_fmac_f32_e32 v4, v30, v30
	v_fmac_f32_e32 v5, v31, v31
	v_fmac_f32_e32 v4, v32, v32
	v_fmac_f32_e32 v5, v33, v33
	v_fmac_f32_e32 v4, v34, v34
	v_fmac_f32_e32 v5, v35, v35
	v_fmac_f32_e32 v4, v36, v36
	v_fmac_f32_e32 v5, v37, v37
	v_fmac_f32_e32 v4, v38, v38
	v_fmac_f32_e32 v5, v39, v39
	v_add_f32_e32 v4, v4, v5
	v_cvt_pk_bf16_f32 v112, v40, v41
	v_cvt_pk_bf16_f32 v113, v42, v43
	v_add_f32_dpp v4, v4, v4 quad_perm:[1,0,3,2] row_mask:0xf bank_mask:0xf
	s_nop 1
	v_add_f32_dpp v4, v4, v4 quad_perm:[2,3,0,1] row_mask:0xf bank_mask:0xf
	s_nop 1
	v_add_f32_dpp v4, v4, v4 row_half_mirror row_mask:0xf bank_mask:0xf
	s_nop 1
	v_add_f32_dpp v4, v4, v4 row_mirror row_mask:0xf bank_mask:0xf
	s_nop 1
	v_readlane_b32 s28, v4, 0
	v_readlane_b32 s29, v4, 16
	v_readlane_b32 s50, v4, 32
	v_readlane_b32 s51, v4, 48
	s_lshl_b32 s13, s14, 11
	s_add_u32 s16, s46, s13
	s_addc_u32 s17, s47, 0
	s_lshl_b32 s13, s14, 9
	s_add_u32 s18, s48, s13
	s_addc_u32 s19, s49, 0
	v_mov_b32_e32 v114, s28
	v_add_f32_e32 v114, s29, v114
	v_add_f32_e32 v114, s50, v114
	v_add_f32_e32 v114, s51, v114
	v_fmamk_f32 v114, v114, 0x3a800000, v3
	v_rsq_f32_e32 v114, v114
	s_nop 0
	v_pk_mul_f32 v[116:117], v[24:25], v[114:115] op_sel_hi:[1,0]
	v_pk_mul_f32 v[118:119], v[26:27], v[114:115] op_sel_hi:[1,0]
	v_pk_mul_f32 v[120:121], v[28:29], v[114:115] op_sel_hi:[1,0]
	v_pk_mul_f32 v[122:123], v[30:31], v[114:115] op_sel_hi:[1,0]
	v_pk_mul_f32 v[124:125], v[32:33], v[114:115] op_sel_hi:[1,0]
	v_pk_mul_f32 v[126:127], v[34:35], v[114:115] op_sel_hi:[1,0]
	v_pk_mul_f32 v[128:129], v[36:37], v[114:115] op_sel_hi:[1,0]
	v_pk_mul_f32 v[130:131], v[38:39], v[114:115] op_sel_hi:[1,0]
	v_pk_mul_f32 v[116:117], v[6:7], v[116:117]
	v_pk_mul_f32 v[118:119], v[8:9], v[118:119]
	v_pk_mul_f32 v[120:121], v[10:11], v[120:121]
	v_pk_mul_f32 v[122:123], v[12:13], v[122:123]
	v_pk_mul_f32 v[124:125], v[14:15], v[124:125]
	v_pk_mul_f32 v[126:127], v[16:17], v[126:127]
	v_pk_mul_f32 v[128:129], v[18:19], v[128:129]
	v_pk_mul_f32 v[130:131], v[20:21], v[130:131]
	v_cvt_pk_bf16_f32 v104, v116, v117
	v_cvt_pk_bf16_f32 v105, v118, v119
	v_cvt_pk_bf16_f32 v106, v120, v121
	v_cvt_pk_bf16_f32 v107, v122, v123
	v_cvt_pk_bf16_f32 v108, v124, v125
	v_cvt_pk_bf16_f32 v109, v126, v127
	v_cvt_pk_bf16_f32 v110, v128, v129
	v_cvt_pk_bf16_f32 v111, v130, v131
	global_store_dwordx2 v2, v[104:105], s[16:17] offset:0
	global_store_dwordx2 v2, v[106:107], s[16:17] offset:512
	global_store_dwordx2 v2, v[108:109], s[16:17] offset:1024
	global_store_dwordx2 v2, v[110:111], s[16:17] offset:1536
	global_store_dwordx2 v2, v[112:113], s[18:19]
	s_cmp_lt_u32 s15, 0x8400
	s_cselect_b32 s12, s15, s0
	s_cmp_lt_u32 s12, 0x8000
	s_cselect_b32 s8, s36, s38
	s_cselect_b32 s9, s37, s39
	s_cselect_b32 s10, s40, s42
	s_cselect_b32 s11, s41, s43
	s_cselect_b32 s13, 0, 0x8000
	s_sub_u32 s12, s12, s13
	s_lshl_b32 s13, s12, 12
	s_add_u32 s8, s8, s13
	s_addc_u32 s9, s9, 0
	s_lshl_b32 s13, s12, 10
	s_add_u32 s10, s10, s13
	s_addc_u32 s11, s11, 0
	global_load_dwordx4 v[24:27], v1, s[8:9] offset:0 nt
	global_load_dwordx4 v[28:31], v1, s[8:9] offset:1024 nt
	global_load_dwordx4 v[32:35], v1, s[8:9] offset:2048 nt
	global_load_dwordx4 v[36:39], v1, s[8:9] offset:3072 nt
	global_load_dwordx4 v[40:43], v1, s[10:11] nt
	s_add_i32 s15, s15, s1
	s_add_i32 s14, s14, s1
	s_waitcnt vmcnt(20)
	v_mul_f32_e32 v4, v44, v44
	v_mul_f32_e32 v5, v45, v45
	v_fmac_f32_e32 v4, v46, v46
	v_fmac_f32_e32 v5, v47, v47
	v_fmac_f32_e32 v4, v48, v48
	v_fmac_f32_e32 v5, v49, v49
	v_fmac_f32_e32 v4, v50, v50
	v_fmac_f32_e32 v5, v51, v51
	v_fmac_f32_e32 v4, v52, v52
	v_fmac_f32_e32 v5, v53, v53
	v_fmac_f32_e32 v4, v54, v54
	v_fmac_f32_e32 v5, v55, v55
	v_fmac_f32_e32 v4, v56, v56
	v_fmac_f32_e32 v5, v57, v57
	v_fmac_f32_e32 v4, v58, v58
	v_fmac_f32_e32 v5, v59, v59
	v_add_f32_e32 v4, v4, v5
	v_cvt_pk_bf16_f32 v112, v60, v61
	v_cvt_pk_bf16_f32 v113, v62, v63
	v_add_f32_dpp v4, v4, v4 quad_perm:[1,0,3,2] row_mask:0xf bank_mask:0xf
	s_nop 1
	v_add_f32_dpp v4, v4, v4 quad_perm:[2,3,0,1] row_mask:0xf bank_mask:0xf
	s_nop 1
	v_add_f32_dpp v4, v4, v4 row_half_mirror row_mask:0xf bank_mask:0xf
	s_nop 1
	v_add_f32_dpp v4, v4, v4 row_mirror row_mask:0xf bank_mask:0xf
	s_nop 1
	v_readlane_b32 s28, v4, 0
	v_readlane_b32 s29, v4, 16
	v_readlane_b32 s50, v4, 32
	v_readlane_b32 s51, v4, 48
	s_lshl_b32 s13, s14, 11
	s_add_u32 s16, s46, s13
	s_addc_u32 s17, s47, 0
	s_lshl_b32 s13, s14, 9
	s_add_u32 s18, s48, s13
	s_addc_u32 s19, s49, 0
	v_mov_b32_e32 v114, s28
	v_add_f32_e32 v114, s29, v114
	v_add_f32_e32 v114, s50, v114
	v_add_f32_e32 v114, s51, v114
	v_fmamk_f32 v114, v114, 0x3a800000, v3
	v_rsq_f32_e32 v114, v114
	s_nop 0
	v_pk_mul_f32 v[116:117], v[44:45], v[114:115] op_sel_hi:[1,0]
	v_pk_mul_f32 v[118:119], v[46:47], v[114:115] op_sel_hi:[1,0]
	v_pk_mul_f32 v[120:121], v[48:49], v[114:115] op_sel_hi:[1,0]
	v_pk_mul_f32 v[122:123], v[50:51], v[114:115] op_sel_hi:[1,0]
	v_pk_mul_f32 v[124:125], v[52:53], v[114:115] op_sel_hi:[1,0]
	v_pk_mul_f32 v[126:127], v[54:55], v[114:115] op_sel_hi:[1,0]
	v_pk_mul_f32 v[128:129], v[56:57], v[114:115] op_sel_hi:[1,0]
	v_pk_mul_f32 v[130:131], v[58:59], v[114:115] op_sel_hi:[1,0]
	v_pk_mul_f32 v[116:117], v[6:7], v[116:117]
	v_pk_mul_f32 v[118:119], v[8:9], v[118:119]
	v_pk_mul_f32 v[120:121], v[10:11], v[120:121]
	v_pk_mul_f32 v[122:123], v[12:13], v[122:123]
	v_pk_mul_f32 v[124:125], v[14:15], v[124:125]
	v_pk_mul_f32 v[126:127], v[16:17], v[126:127]
	v_pk_mul_f32 v[128:129], v[18:19], v[128:129]
	v_pk_mul_f32 v[130:131], v[20:21], v[130:131]
	v_cvt_pk_bf16_f32 v104, v116, v117
	v_cvt_pk_bf16_f32 v105, v118, v119
	v_cvt_pk_bf16_f32 v106, v120, v121
	v_cvt_pk_bf16_f32 v107, v122, v123
	v_cvt_pk_bf16_f32 v108, v124, v125
	v_cvt_pk_bf16_f32 v109, v126, v127
	v_cvt_pk_bf16_f32 v110, v128, v129
	v_cvt_pk_bf16_f32 v111, v130, v131
	global_store_dwordx2 v2, v[104:105], s[16:17] offset:0
	global_store_dwordx2 v2, v[106:107], s[16:17] offset:512
	global_store_dwordx2 v2, v[108:109], s[16:17] offset:1024
	global_store_dwordx2 v2, v[110:111], s[16:17] offset:1536
	global_store_dwordx2 v2, v[112:113], s[18:19]
	s_cmp_lt_u32 s15, 0x8400
	s_cselect_b32 s12, s15, s0
	s_cmp_lt_u32 s12, 0x8000
	s_cselect_b32 s8, s36, s38
	s_cselect_b32 s9, s37, s39
	s_cselect_b32 s10, s40, s42
	s_cselect_b32 s11, s41, s43
	s_cselect_b32 s13, 0, 0x8000
	s_sub_u32 s12, s12, s13
	s_lshl_b32 s13, s12, 12
	s_add_u32 s8, s8, s13
	s_addc_u32 s9, s9, 0
	s_lshl_b32 s13, s12, 10
	s_add_u32 s10, s10, s13
	s_addc_u32 s11, s11, 0
	global_load_dwordx4 v[44:47], v1, s[8:9] offset:0 nt
	global_load_dwordx4 v[48:51], v1, s[8:9] offset:1024 nt
	global_load_dwordx4 v[52:55], v1, s[8:9] offset:2048 nt
	global_load_dwordx4 v[56:59], v1, s[8:9] offset:3072 nt
	global_load_dwordx4 v[60:63], v1, s[10:11] nt
	s_add_i32 s15, s15, s1
	s_add_i32 s14, s14, s1
	s_waitcnt vmcnt(25)
	v_mul_f32_e32 v4, v64, v64
	v_mul_f32_e32 v5, v65, v65
	v_fmac_f32_e32 v4, v66, v66
	v_fmac_f32_e32 v5, v67, v67
	v_fmac_f32_e32 v4, v68, v68
	v_fmac_f32_e32 v5, v69, v69
	v_fmac_f32_e32 v4, v70, v70
	v_fmac_f32_e32 v5, v71, v71
	v_fmac_f32_e32 v4, v72, v72
	v_fmac_f32_e32 v5, v73, v73
	v_fmac_f32_e32 v4, v74, v74
	v_fmac_f32_e32 v5, v75, v75
	v_fmac_f32_e32 v4, v76, v76
	v_fmac_f32_e32 v5, v77, v77
	v_fmac_f32_e32 v4, v78, v78
	v_fmac_f32_e32 v5, v79, v79
	v_add_f32_e32 v4, v4, v5
	v_cvt_pk_bf16_f32 v112, v80, v81
	v_cvt_pk_bf16_f32 v113, v82, v83
	v_add_f32_dpp v4, v4, v4 quad_perm:[1,0,3,2] row_mask:0xf bank_mask:0xf
	s_nop 1
	v_add_f32_dpp v4, v4, v4 quad_perm:[2,3,0,1] row_mask:0xf bank_mask:0xf
	s_nop 1
	v_add_f32_dpp v4, v4, v4 row_half_mirror row_mask:0xf bank_mask:0xf
	s_nop 1
	v_add_f32_dpp v4, v4, v4 row_mirror row_mask:0xf bank_mask:0xf
	s_nop 1
	v_readlane_b32 s28, v4, 0
	v_readlane_b32 s29, v4, 16
	v_readlane_b32 s50, v4, 32
	v_readlane_b32 s51, v4, 48
	s_lshl_b32 s13, s14, 11
	s_add_u32 s16, s46, s13
	s_addc_u32 s17, s47, 0
	s_lshl_b32 s13, s14, 9
	s_add_u32 s18, s48, s13
	s_addc_u32 s19, s49, 0
	v_mov_b32_e32 v114, s28
	v_add_f32_e32 v114, s29, v114
	v_add_f32_e32 v114, s50, v114
	v_add_f32_e32 v114, s51, v114
	v_fmamk_f32 v114, v114, 0x3a800000, v3
	v_rsq_f32_e32 v114, v114
	s_nop 0
	v_pk_mul_f32 v[116:117], v[64:65], v[114:115] op_sel_hi:[1,0]
	v_pk_mul_f32 v[118:119], v[66:67], v[114:115] op_sel_hi:[1,0]
	v_pk_mul_f32 v[120:121], v[68:69], v[114:115] op_sel_hi:[1,0]
	v_pk_mul_f32 v[122:123], v[70:71], v[114:115] op_sel_hi:[1,0]
	v_pk_mul_f32 v[124:125], v[72:73], v[114:115] op_sel_hi:[1,0]
	v_pk_mul_f32 v[126:127], v[74:75], v[114:115] op_sel_hi:[1,0]
	v_pk_mul_f32 v[128:129], v[76:77], v[114:115] op_sel_hi:[1,0]
	v_pk_mul_f32 v[130:131], v[78:79], v[114:115] op_sel_hi:[1,0]
	v_pk_mul_f32 v[116:117], v[6:7], v[116:117]
	v_pk_mul_f32 v[118:119], v[8:9], v[118:119]
	v_pk_mul_f32 v[120:121], v[10:11], v[120:121]
	v_pk_mul_f32 v[122:123], v[12:13], v[122:123]
	v_pk_mul_f32 v[124:125], v[14:15], v[124:125]
	v_pk_mul_f32 v[126:127], v[16:17], v[126:127]
	v_pk_mul_f32 v[128:129], v[18:19], v[128:129]
	v_pk_mul_f32 v[130:131], v[20:21], v[130:131]
	v_cvt_pk_bf16_f32 v104, v116, v117
	v_cvt_pk_bf16_f32 v105, v118, v119
	v_cvt_pk_bf16_f32 v106, v120, v121
	v_cvt_pk_bf16_f32 v107, v122, v123
	v_cvt_pk_bf16_f32 v108, v124, v125
	v_cvt_pk_bf16_f32 v109, v126, v127
	v_cvt_pk_bf16_f32 v110, v128, v129
	v_cvt_pk_bf16_f32 v111, v130, v131
	global_store_dwordx2 v2, v[104:105], s[16:17] offset:0
	global_store_dwordx2 v2, v[106:107], s[16:17] offset:512
	global_store_dwordx2 v2, v[108:109], s[16:17] offset:1024
	global_store_dwordx2 v2, v[110:111], s[16:17] offset:1536
	global_store_dwordx2 v2, v[112:113], s[18:19]
	s_cmp_lt_u32 s15, 0x8400
	s_cselect_b32 s12, s15, s0
	s_cmp_lt_u32 s12, 0x8000
	s_cselect_b32 s8, s36, s38
	s_cselect_b32 s9, s37, s39
	s_cselect_b32 s10, s40, s42
	s_cselect_b32 s11, s41, s43
	s_cselect_b32 s13, 0, 0x8000
	s_sub_u32 s12, s12, s13
	s_lshl_b32 s13, s12, 12
	s_add_u32 s8, s8, s13
	s_addc_u32 s9, s9, 0
	s_lshl_b32 s13, s12, 10
	s_add_u32 s10, s10, s13
	s_addc_u32 s11, s11, 0
	global_load_dwordx4 v[64:67], v1, s[8:9] offset:0 nt
	global_load_dwordx4 v[68:71], v1, s[8:9] offset:1024 nt
	global_load_dwordx4 v[72:75], v1, s[8:9] offset:2048 nt
	global_load_dwordx4 v[76:79], v1, s[8:9] offset:3072 nt
	global_load_dwordx4 v[80:83], v1, s[10:11] nt
	s_add_i32 s15, s15, s1
	s_add_i32 s14, s14, s1
	s_waitcnt vmcnt(30)
	v_mul_f32_e32 v4, v84, v84
	v_mul_f32_e32 v5, v85, v85
	v_fmac_f32_e32 v4, v86, v86
	v_fmac_f32_e32 v5, v87, v87
	v_fmac_f32_e32 v4, v88, v88
	v_fmac_f32_e32 v5, v89, v89
	v_fmac_f32_e32 v4, v90, v90
	v_fmac_f32_e32 v5, v91, v91
	v_fmac_f32_e32 v4, v92, v92
	v_fmac_f32_e32 v5, v93, v93
	v_fmac_f32_e32 v4, v94, v94
	v_fmac_f32_e32 v5, v95, v95
	v_fmac_f32_e32 v4, v96, v96
	v_fmac_f32_e32 v5, v97, v97
	v_fmac_f32_e32 v4, v98, v98
	v_fmac_f32_e32 v5, v99, v99
	v_add_f32_e32 v4, v4, v5
	v_cvt_pk_bf16_f32 v112, v100, v101
	v_cvt_pk_bf16_f32 v113, v102, v103
	v_add_f32_dpp v4, v4, v4 quad_perm:[1,0,3,2] row_mask:0xf bank_mask:0xf
	s_nop 1
	v_add_f32_dpp v4, v4, v4 quad_perm:[2,3,0,1] row_mask:0xf bank_mask:0xf
	s_nop 1
	v_add_f32_dpp v4, v4, v4 row_half_mirror row_mask:0xf bank_mask:0xf
	s_nop 1
	v_add_f32_dpp v4, v4, v4 row_mirror row_mask:0xf bank_mask:0xf
	s_nop 1
	v_readlane_b32 s28, v4, 0
	v_readlane_b32 s29, v4, 16
	v_readlane_b32 s50, v4, 32
	v_readlane_b32 s51, v4, 48
	s_lshl_b32 s13, s14, 11
	s_add_u32 s16, s46, s13
	s_addc_u32 s17, s47, 0
	s_lshl_b32 s13, s14, 9
	s_add_u32 s18, s48, s13
	s_addc_u32 s19, s49, 0
	v_mov_b32_e32 v114, s28
	v_add_f32_e32 v114, s29, v114
	v_add_f32_e32 v114, s50, v114
	v_add_f32_e32 v114, s51, v114
	v_fmamk_f32 v114, v114, 0x3a800000, v3
	v_rsq_f32_e32 v114, v114
	s_nop 0
	v_pk_mul_f32 v[116:117], v[84:85], v[114:115] op_sel_hi:[1,0]
	v_pk_mul_f32 v[118:119], v[86:87], v[114:115] op_sel_hi:[1,0]
	v_pk_mul_f32 v[120:121], v[88:89], v[114:115] op_sel_hi:[1,0]
	v_pk_mul_f32 v[122:123], v[90:91], v[114:115] op_sel_hi:[1,0]
	v_pk_mul_f32 v[124:125], v[92:93], v[114:115] op_sel_hi:[1,0]
	v_pk_mul_f32 v[126:127], v[94:95], v[114:115] op_sel_hi:[1,0]
	v_pk_mul_f32 v[128:129], v[96:97], v[114:115] op_sel_hi:[1,0]
	v_pk_mul_f32 v[130:131], v[98:99], v[114:115] op_sel_hi:[1,0]
	v_pk_mul_f32 v[116:117], v[6:7], v[116:117]
	v_pk_mul_f32 v[118:119], v[8:9], v[118:119]
	v_pk_mul_f32 v[120:121], v[10:11], v[120:121]
	v_pk_mul_f32 v[122:123], v[12:13], v[122:123]
	v_pk_mul_f32 v[124:125], v[14:15], v[124:125]
	v_pk_mul_f32 v[126:127], v[16:17], v[126:127]
	v_pk_mul_f32 v[128:129], v[18:19], v[128:129]
	v_pk_mul_f32 v[130:131], v[20:21], v[130:131]
	v_cvt_pk_bf16_f32 v104, v116, v117
	v_cvt_pk_bf16_f32 v105, v118, v119
	v_cvt_pk_bf16_f32 v106, v120, v121
	v_cvt_pk_bf16_f32 v107, v122, v123
	v_cvt_pk_bf16_f32 v108, v124, v125
	v_cvt_pk_bf16_f32 v109, v126, v127
	v_cvt_pk_bf16_f32 v110, v128, v129
	v_cvt_pk_bf16_f32 v111, v130, v131
	global_store_dwordx2 v2, v[104:105], s[16:17] offset:0
	global_store_dwordx2 v2, v[106:107], s[16:17] offset:512
	global_store_dwordx2 v2, v[108:109], s[16:17] offset:1024
	global_store_dwordx2 v2, v[110:111], s[16:17] offset:1536
	global_store_dwordx2 v2, v[112:113], s[18:19]
	s_cmp_lt_u32 s15, 0x8400
	s_cselect_b32 s12, s15, s0
	s_cmp_lt_u32 s12, 0x8000
	s_cselect_b32 s8, s36, s38
	s_cselect_b32 s9, s37, s39
	s_cselect_b32 s10, s40, s42
	s_cselect_b32 s11, s41, s43
	s_cselect_b32 s13, 0, 0x8000
	s_sub_u32 s12, s12, s13
	s_lshl_b32 s13, s12, 12
	s_add_u32 s8, s8, s13
	s_addc_u32 s9, s9, 0
	s_lshl_b32 s13, s12, 10
	s_add_u32 s10, s10, s13
	s_addc_u32 s11, s11, 0
	global_load_dwordx4 v[84:87], v1, s[8:9] offset:0 nt
	global_load_dwordx4 v[88:91], v1, s[8:9] offset:1024 nt
	global_load_dwordx4 v[92:95], v1, s[8:9] offset:2048 nt
	global_load_dwordx4 v[96:99], v1, s[8:9] offset:3072 nt
	global_load_dwordx4 v[100:103], v1, s[10:11] nt
	s_add_i32 s15, s15, s1
	s_add_i32 s14, s14, s1
	s_mov_b32 s0, s14
.Lxn_loop:
	s_mul_i32 s8, s1, 3
	s_add_i32 s8, s8, s0
	s_cmp_lt_u32 s8, 0x8400
	s_cbranch_scc0 .Lxn_tail
	s_waitcnt vmcnt(30)
	v_mul_f32_e32 v4, v24, v24
	v_mul_f32_e32 v5, v25, v25
	v_fmac_f32_e32 v4, v26, v26
	v_fmac_f32_e32 v5, v27, v27
	v_fmac_f32_e32 v4, v28, v28
	v_fmac_f32_e32 v5, v29, v29
	v_fmac_f32_e32 v4, v30, v30
	v_fmac_f32_e32 v5, v31, v31
	v_fmac_f32_e32 v4, v32, v32
	v_fmac_f32_e32 v5, v33, v33
	v_fmac_f32_e32 v4, v34, v34
	v_fmac_f32_e32 v5, v35, v35
	v_fmac_f32_e32 v4, v36, v36
	v_fmac_f32_e32 v5, v37, v37
	v_fmac_f32_e32 v4, v38, v38
	v_fmac_f32_e32 v5, v39, v39
	v_add_f32_e32 v4, v4, v5
	v_cvt_pk_bf16_f32 v112, v40, v41
	v_cvt_pk_bf16_f32 v113, v42, v43
	v_add_f32_dpp v4, v4, v4 quad_perm:[1,0,3,2] row_mask:0xf bank_mask:0xf
	s_nop 1
	v_add_f32_dpp v4, v4, v4 quad_perm:[2,3,0,1] row_mask:0xf bank_mask:0xf
	s_nop 1
	v_add_f32_dpp v4, v4, v4 row_half_mirror row_mask:0xf bank_mask:0xf
	s_nop 1
	v_add_f32_dpp v4, v4, v4 row_mirror row_mask:0xf bank_mask:0xf
	s_nop 1
	v_readlane_b32 s28, v4, 0
	v_readlane_b32 s29, v4, 16
	v_readlane_b32 s50, v4, 32
	v_readlane_b32 s51, v4, 48
	s_lshl_b32 s13, s14, 11
	s_add_u32 s16, s46, s13
	s_addc_u32 s17, s47, 0
	s_lshl_b32 s13, s14, 9
	s_add_u32 s18, s48, s13
	s_addc_u32 s19, s49, 0
	v_mov_b32_e32 v114, s28
	v_add_f32_e32 v114, s29, v114
	v_add_f32_e32 v114, s50, v114
	v_add_f32_e32 v114, s51, v114
	v_fmamk_f32 v114, v114, 0x3a800000, v3
	v_rsq_f32_e32 v114, v114
	s_nop 0
	v_pk_mul_f32 v[116:117], v[24:25], v[114:115] op_sel_hi:[1,0]
	v_pk_mul_f32 v[118:119], v[26:27], v[114:115] op_sel_hi:[1,0]
	v_pk_mul_f32 v[120:121], v[28:29], v[114:115] op_sel_hi:[1,0]
	v_pk_mul_f32 v[122:123], v[30:31], v[114:115] op_sel_hi:[1,0]
	v_pk_mul_f32 v[124:125], v[32:33], v[114:115] op_sel_hi:[1,0]
	v_pk_mul_f32 v[126:127], v[34:35], v[114:115] op_sel_hi:[1,0]
	v_pk_mul_f32 v[128:129], v[36:37], v[114:115] op_sel_hi:[1,0]
	v_pk_mul_f32 v[130:131], v[38:39], v[114:115] op_sel_hi:[1,0]
	v_pk_mul_f32 v[116:117], v[6:7], v[116:117]
	v_pk_mul_f32 v[118:119], v[8:9], v[118:119]
	v_pk_mul_f32 v[120:121], v[10:11], v[120:121]
	v_pk_mul_f32 v[122:123], v[12:13], v[122:123]
	v_pk_mul_f32 v[124:125], v[14:15], v[124:125]
	v_pk_mul_f32 v[126:127], v[16:17], v[126:127]
	v_pk_mul_f32 v[128:129], v[18:19], v[128:129]
	v_pk_mul_f32 v[130:131], v[20:21], v[130:131]
	v_cvt_pk_bf16_f32 v104, v116, v117
	v_cvt_pk_bf16_f32 v105, v118, v119
	v_cvt_pk_bf16_f32 v106, v120, v121
	v_cvt_pk_bf16_f32 v107, v122, v123
	v_cvt_pk_bf16_f32 v108, v124, v125
	v_cvt_pk_bf16_f32 v109, v126, v127
	v_cvt_pk_bf16_f32 v110, v128, v129
	v_cvt_pk_bf16_f32 v111, v130, v131
	global_store_dwordx2 v2, v[104:105], s[16:17] offset:0
	global_store_dwordx2 v2, v[106:107], s[16:17] offset:512
	global_store_dwordx2 v2, v[108:109], s[16:17] offset:1024
	global_store_dwordx2 v2, v[110:111], s[16:17] offset:1536
	global_store_dwordx2 v2, v[112:113], s[18:19]
	s_cmp_lt_u32 s15, 0x8400
	s_cselect_b32 s12, s15, s0
	s_cmp_lt_u32 s12, 0x8000
	s_cselect_b32 s8, s36, s38
	s_cselect_b32 s9, s37, s39
	s_cselect_b32 s10, s40, s42
	s_cselect_b32 s11, s41, s43
	s_cselect_b32 s13, 0, 0x8000
	s_sub_u32 s12, s12, s13
	s_lshl_b32 s13, s12, 12
	s_add_u32 s8, s8, s13
	s_addc_u32 s9, s9, 0
	s_lshl_b32 s13, s12, 10
	s_add_u32 s10, s10, s13
	s_addc_u32 s11, s11, 0
	global_load_dwordx4 v[24:27], v1, s[8:9] offset:0 nt
	global_load_dwordx4 v[28:31], v1, s[8:9] offset:1024 nt
	global_load_dwordx4 v[32:35], v1, s[8:9] offset:2048 nt
	global_load_dwordx4 v[36:39], v1, s[8:9] offset:3072 nt
	global_load_dwordx4 v[40:43], v1, s[10:11] nt
	s_add_i32 s15, s15, s1
	s_add_i32 s14, s14, s1
	s_waitcnt vmcnt(30)
	v_mul_f32_e32 v4, v44, v44
	v_mul_f32_e32 v5, v45, v45
	v_fmac_f32_e32 v4, v46, v46
	v_fmac_f32_e32 v5, v47, v47
	v_fmac_f32_e32 v4, v48, v48
	v_fmac_f32_e32 v5, v49, v49
	v_fmac_f32_e32 v4, v50, v50
	v_fmac_f32_e32 v5, v51, v51
	v_fmac_f32_e32 v4, v52, v52
	v_fmac_f32_e32 v5, v53, v53
	v_fmac_f32_e32 v4, v54, v54
	v_fmac_f32_e32 v5, v55, v55
	v_fmac_f32_e32 v4, v56, v56
	v_fmac_f32_e32 v5, v57, v57
	v_fmac_f32_e32 v4, v58, v58
	v_fmac_f32_e32 v5, v59, v59
	v_add_f32_e32 v4, v4, v5
	v_cvt_pk_bf16_f32 v112, v60, v61
	v_cvt_pk_bf16_f32 v113, v62, v63
	v_add_f32_dpp v4, v4, v4 quad_perm:[1,0,3,2] row_mask:0xf bank_mask:0xf
	s_nop 1
	v_add_f32_dpp v4, v4, v4 quad_perm:[2,3,0,1] row_mask:0xf bank_mask:0xf
	s_nop 1
	v_add_f32_dpp v4, v4, v4 row_half_mirror row_mask:0xf bank_mask:0xf
	s_nop 1
	v_add_f32_dpp v4, v4, v4 row_mirror row_mask:0xf bank_mask:0xf
	s_nop 1
	v_readlane_b32 s28, v4, 0
	v_readlane_b32 s29, v4, 16
	v_readlane_b32 s50, v4, 32
	v_readlane_b32 s51, v4, 48
	s_lshl_b32 s13, s14, 11
	s_add_u32 s16, s46, s13
	s_addc_u32 s17, s47, 0
	s_lshl_b32 s13, s14, 9
	s_add_u32 s18, s48, s13
	s_addc_u32 s19, s49, 0
	v_mov_b32_e32 v114, s28
	v_add_f32_e32 v114, s29, v114
	v_add_f32_e32 v114, s50, v114
	v_add_f32_e32 v114, s51, v114
	v_fmamk_f32 v114, v114, 0x3a800000, v3
	v_rsq_f32_e32 v114, v114
	s_nop 0
	v_pk_mul_f32 v[116:117], v[44:45], v[114:115] op_sel_hi:[1,0]
	v_pk_mul_f32 v[118:119], v[46:47], v[114:115] op_sel_hi:[1,0]
	v_pk_mul_f32 v[120:121], v[48:49], v[114:115] op_sel_hi:[1,0]
	v_pk_mul_f32 v[122:123], v[50:51], v[114:115] op_sel_hi:[1,0]
	v_pk_mul_f32 v[124:125], v[52:53], v[114:115] op_sel_hi:[1,0]
	v_pk_mul_f32 v[126:127], v[54:55], v[114:115] op_sel_hi:[1,0]
	v_pk_mul_f32 v[128:129], v[56:57], v[114:115] op_sel_hi:[1,0]
	v_pk_mul_f32 v[130:131], v[58:59], v[114:115] op_sel_hi:[1,0]
	v_pk_mul_f32 v[116:117], v[6:7], v[116:117]
	v_pk_mul_f32 v[118:119], v[8:9], v[118:119]
	v_pk_mul_f32 v[120:121], v[10:11], v[120:121]
	v_pk_mul_f32 v[122:123], v[12:13], v[122:123]
	v_pk_mul_f32 v[124:125], v[14:15], v[124:125]
	v_pk_mul_f32 v[126:127], v[16:17], v[126:127]
	v_pk_mul_f32 v[128:129], v[18:19], v[128:129]
	v_pk_mul_f32 v[130:131], v[20:21], v[130:131]
	v_cvt_pk_bf16_f32 v104, v116, v117
	v_cvt_pk_bf16_f32 v105, v118, v119
	v_cvt_pk_bf16_f32 v106, v120, v121
	v_cvt_pk_bf16_f32 v107, v122, v123
	v_cvt_pk_bf16_f32 v108, v124, v125
	v_cvt_pk_bf16_f32 v109, v126, v127
	v_cvt_pk_bf16_f32 v110, v128, v129
	v_cvt_pk_bf16_f32 v111, v130, v131
	global_store_dwordx2 v2, v[104:105], s[16:17] offset:0
	global_store_dwordx2 v2, v[106:107], s[16:17] offset:512
	global_store_dwordx2 v2, v[108:109], s[16:17] offset:1024
	global_store_dwordx2 v2, v[110:111], s[16:17] offset:1536
	global_store_dwordx2 v2, v[112:113], s[18:19]
	s_cmp_lt_u32 s15, 0x8400
	s_cselect_b32 s12, s15, s0
	s_cmp_lt_u32 s12, 0x8000
	s_cselect_b32 s8, s36, s38
	s_cselect_b32 s9, s37, s39
	s_cselect_b32 s10, s40, s42
	s_cselect_b32 s11, s41, s43
	s_cselect_b32 s13, 0, 0x8000
	s_sub_u32 s12, s12, s13
	s_lshl_b32 s13, s12, 12
	s_add_u32 s8, s8, s13
	s_addc_u32 s9, s9, 0
	s_lshl_b32 s13, s12, 10
	s_add_u32 s10, s10, s13
	s_addc_u32 s11, s11, 0
	global_load_dwordx4 v[44:47], v1, s[8:9] offset:0 nt
	global_load_dwordx4 v[48:51], v1, s[8:9] offset:1024 nt
	global_load_dwordx4 v[52:55], v1, s[8:9] offset:2048 nt
	global_load_dwordx4 v[56:59], v1, s[8:9] offset:3072 nt
	global_load_dwordx4 v[60:63], v1, s[10:11] nt
	s_add_i32 s15, s15, s1
	s_add_i32 s14, s14, s1
	s_waitcnt vmcnt(30)
	v_mul_f32_e32 v4, v64, v64
	v_mul_f32_e32 v5, v65, v65
	v_fmac_f32_e32 v4, v66, v66
	v_fmac_f32_e32 v5, v67, v67
	v_fmac_f32_e32 v4, v68, v68
	v_fmac_f32_e32 v5, v69, v69
	v_fmac_f32_e32 v4, v70, v70
	v_fmac_f32_e32 v5, v71, v71
	v_fmac_f32_e32 v4, v72, v72
	v_fmac_f32_e32 v5, v73, v73
	v_fmac_f32_e32 v4, v74, v74
	v_fmac_f32_e32 v5, v75, v75
	v_fmac_f32_e32 v4, v76, v76
	v_fmac_f32_e32 v5, v77, v77
	v_fmac_f32_e32 v4, v78, v78
	v_fmac_f32_e32 v5, v79, v79
	v_add_f32_e32 v4, v4, v5
	v_cvt_pk_bf16_f32 v112, v80, v81
	v_cvt_pk_bf16_f32 v113, v82, v83
	v_add_f32_dpp v4, v4, v4 quad_perm:[1,0,3,2] row_mask:0xf bank_mask:0xf
	s_nop 1
	v_add_f32_dpp v4, v4, v4 quad_perm:[2,3,0,1] row_mask:0xf bank_mask:0xf
	s_nop 1
	v_add_f32_dpp v4, v4, v4 row_half_mirror row_mask:0xf bank_mask:0xf
	s_nop 1
	v_add_f32_dpp v4, v4, v4 row_mirror row_mask:0xf bank_mask:0xf
	s_nop 1
	v_readlane_b32 s28, v4, 0
	v_readlane_b32 s29, v4, 16
	v_readlane_b32 s50, v4, 32
	v_readlane_b32 s51, v4, 48
	s_lshl_b32 s13, s14, 11
	s_add_u32 s16, s46, s13
	s_addc_u32 s17, s47, 0
	s_lshl_b32 s13, s14, 9
	s_add_u32 s18, s48, s13
	s_addc_u32 s19, s49, 0
	v_mov_b32_e32 v114, s28
	v_add_f32_e32 v114, s29, v114
	v_add_f32_e32 v114, s50, v114
	v_add_f32_e32 v114, s51, v114
	v_fmamk_f32 v114, v114, 0x3a800000, v3
	v_rsq_f32_e32 v114, v114
	s_nop 0
	v_pk_mul_f32 v[116:117], v[64:65], v[114:115] op_sel_hi:[1,0]
	v_pk_mul_f32 v[118:119], v[66:67], v[114:115] op_sel_hi:[1,0]
	v_pk_mul_f32 v[120:121], v[68:69], v[114:115] op_sel_hi:[1,0]
	v_pk_mul_f32 v[122:123], v[70:71], v[114:115] op_sel_hi:[1,0]
	v_pk_mul_f32 v[124:125], v[72:73], v[114:115] op_sel_hi:[1,0]
	v_pk_mul_f32 v[126:127], v[74:75], v[114:115] op_sel_hi:[1,0]
	v_pk_mul_f32 v[128:129], v[76:77], v[114:115] op_sel_hi:[1,0]
	v_pk_mul_f32 v[130:131], v[78:79], v[114:115] op_sel_hi:[1,0]
	v_pk_mul_f32 v[116:117], v[6:7], v[116:117]
	v_pk_mul_f32 v[118:119], v[8:9], v[118:119]
	v_pk_mul_f32 v[120:121], v[10:11], v[120:121]
	v_pk_mul_f32 v[122:123], v[12:13], v[122:123]
	v_pk_mul_f32 v[124:125], v[14:15], v[124:125]
	v_pk_mul_f32 v[126:127], v[16:17], v[126:127]
	v_pk_mul_f32 v[128:129], v[18:19], v[128:129]
	v_pk_mul_f32 v[130:131], v[20:21], v[130:131]
	v_cvt_pk_bf16_f32 v104, v116, v117
	v_cvt_pk_bf16_f32 v105, v118, v119
	v_cvt_pk_bf16_f32 v106, v120, v121
	v_cvt_pk_bf16_f32 v107, v122, v123
	v_cvt_pk_bf16_f32 v108, v124, v125
	v_cvt_pk_bf16_f32 v109, v126, v127
	v_cvt_pk_bf16_f32 v110, v128, v129
	v_cvt_pk_bf16_f32 v111, v130, v131
	global_store_dwordx2 v2, v[104:105], s[16:17] offset:0
	global_store_dwordx2 v2, v[106:107], s[16:17] offset:512
	global_store_dwordx2 v2, v[108:109], s[16:17] offset:1024
	global_store_dwordx2 v2, v[110:111], s[16:17] offset:1536
	global_store_dwordx2 v2, v[112:113], s[18:19]
	s_cmp_lt_u32 s15, 0x8400
	s_cselect_b32 s12, s15, s0
	s_cmp_lt_u32 s12, 0x8000
	s_cselect_b32 s8, s36, s38
	s_cselect_b32 s9, s37, s39
	s_cselect_b32 s10, s40, s42
	s_cselect_b32 s11, s41, s43
	s_cselect_b32 s13, 0, 0x8000
	s_sub_u32 s12, s12, s13
	s_lshl_b32 s13, s12, 12
	s_add_u32 s8, s8, s13
	s_addc_u32 s9, s9, 0
	s_lshl_b32 s13, s12, 10
	s_add_u32 s10, s10, s13
	s_addc_u32 s11, s11, 0
	global_load_dwordx4 v[64:67], v1, s[8:9] offset:0 nt
	global_load_dwordx4 v[68:71], v1, s[8:9] offset:1024 nt
	global_load_dwordx4 v[72:75], v1, s[8:9] offset:2048 nt
	global_load_dwordx4 v[76:79], v1, s[8:9] offset:3072 nt
	global_load_dwordx4 v[80:83], v1, s[10:11] nt
	s_add_i32 s15, s15, s1
	s_add_i32 s14, s14, s1
	s_waitcnt vmcnt(30)
	v_mul_f32_e32 v4, v84, v84
	v_mul_f32_e32 v5, v85, v85
	v_fmac_f32_e32 v4, v86, v86
	v_fmac_f32_e32 v5, v87, v87
	v_fmac_f32_e32 v4, v88, v88
	v_fmac_f32_e32 v5, v89, v89
	v_fmac_f32_e32 v4, v90, v90
	v_fmac_f32_e32 v5, v91, v91
	v_fmac_f32_e32 v4, v92, v92
	v_fmac_f32_e32 v5, v93, v93
	v_fmac_f32_e32 v4, v94, v94
	v_fmac_f32_e32 v5, v95, v95
	v_fmac_f32_e32 v4, v96, v96
	v_fmac_f32_e32 v5, v97, v97
	v_fmac_f32_e32 v4, v98, v98
	v_fmac_f32_e32 v5, v99, v99
	v_add_f32_e32 v4, v4, v5
	v_cvt_pk_bf16_f32 v112, v100, v101
	v_cvt_pk_bf16_f32 v113, v102, v103
	v_add_f32_dpp v4, v4, v4 quad_perm:[1,0,3,2] row_mask:0xf bank_mask:0xf
	s_nop 1
	v_add_f32_dpp v4, v4, v4 quad_perm:[2,3,0,1] row_mask:0xf bank_mask:0xf
	s_nop 1
	v_add_f32_dpp v4, v4, v4 row_half_mirror row_mask:0xf bank_mask:0xf
	s_nop 1
	v_add_f32_dpp v4, v4, v4 row_mirror row_mask:0xf bank_mask:0xf
	s_nop 1
	v_readlane_b32 s28, v4, 0
	v_readlane_b32 s29, v4, 16
	v_readlane_b32 s50, v4, 32
	v_readlane_b32 s51, v4, 48
	s_lshl_b32 s13, s14, 11
	s_add_u32 s16, s46, s13
	s_addc_u32 s17, s47, 0
	s_lshl_b32 s13, s14, 9
	s_add_u32 s18, s48, s13
	s_addc_u32 s19, s49, 0
	v_mov_b32_e32 v114, s28
	v_add_f32_e32 v114, s29, v114
	v_add_f32_e32 v114, s50, v114
	v_add_f32_e32 v114, s51, v114
	v_fmamk_f32 v114, v114, 0x3a800000, v3
	v_rsq_f32_e32 v114, v114
	s_nop 0
	v_pk_mul_f32 v[116:117], v[84:85], v[114:115] op_sel_hi:[1,0]
	v_pk_mul_f32 v[118:119], v[86:87], v[114:115] op_sel_hi:[1,0]
	v_pk_mul_f32 v[120:121], v[88:89], v[114:115] op_sel_hi:[1,0]
	v_pk_mul_f32 v[122:123], v[90:91], v[114:115] op_sel_hi:[1,0]
	v_pk_mul_f32 v[124:125], v[92:93], v[114:115] op_sel_hi:[1,0]
	v_pk_mul_f32 v[126:127], v[94:95], v[114:115] op_sel_hi:[1,0]
	v_pk_mul_f32 v[128:129], v[96:97], v[114:115] op_sel_hi:[1,0]
	v_pk_mul_f32 v[130:131], v[98:99], v[114:115] op_sel_hi:[1,0]
	v_pk_mul_f32 v[116:117], v[6:7], v[116:117]
	v_pk_mul_f32 v[118:119], v[8:9], v[118:119]
	v_pk_mul_f32 v[120:121], v[10:11], v[120:121]
	v_pk_mul_f32 v[122:123], v[12:13], v[122:123]
	v_pk_mul_f32 v[124:125], v[14:15], v[124:125]
	v_pk_mul_f32 v[126:127], v[16:17], v[126:127]
	v_pk_mul_f32 v[128:129], v[18:19], v[128:129]
	v_pk_mul_f32 v[130:131], v[20:21], v[130:131]
	v_cvt_pk_bf16_f32 v104, v116, v117
	v_cvt_pk_bf16_f32 v105, v118, v119
	v_cvt_pk_bf16_f32 v106, v120, v121
	v_cvt_pk_bf16_f32 v107, v122, v123
	v_cvt_pk_bf16_f32 v108, v124, v125
	v_cvt_pk_bf16_f32 v109, v126, v127
	v_cvt_pk_bf16_f32 v110, v128, v129
	v_cvt_pk_bf16_f32 v111, v130, v131
	global_store_dwordx2 v2, v[104:105], s[16:17] offset:0
	global_store_dwordx2 v2, v[106:107], s[16:17] offset:512
	global_store_dwordx2 v2, v[108:109], s[16:17] offset:1024
	global_store_dwordx2 v2, v[110:111], s[16:17] offset:1536
	global_store_dwordx2 v2, v[112:113], s[18:19]
	s_cmp_lt_u32 s15, 0x8400
	s_cselect_b32 s12, s15, s0
	s_cmp_lt_u32 s12, 0x8000
	s_cselect_b32 s8, s36, s38
	s_cselect_b32 s9, s37, s39
	s_cselect_b32 s10, s40, s42
	s_cselect_b32 s11, s41, s43
	s_cselect_b32 s13, 0, 0x8000
	s_sub_u32 s12, s12, s13
	s_lshl_b32 s13, s12, 12
	s_add_u32 s8, s8, s13
	s_addc_u32 s9, s9, 0
	s_lshl_b32 s13, s12, 10
	s_add_u32 s10, s10, s13
	s_addc_u32 s11, s11, 0
	global_load_dwordx4 v[84:87], v1, s[8:9] offset:0 nt
	global_load_dwordx4 v[88:91], v1, s[8:9] offset:1024 nt
	global_load_dwordx4 v[92:95], v1, s[8:9] offset:2048 nt
	global_load_dwordx4 v[96:99], v1, s[8:9] offset:3072 nt
	global_load_dwordx4 v[100:103], v1, s[10:11] nt
	s_add_i32 s15, s15, s1
	s_add_i32 s14, s14, s1
	s_mov_b32 s0, s14
	s_branch .Lxn_loop
